# IN-phase mlp weight conversion: next tile of the block touched ahead (guarded to stay inside the matrix)
# speedup vs baseline: 1.0011x; 1.0003x over previous
; __device__ __forceinline__ void cvt_matrix(const float* __restrict__ src, int ldsrc, int K, int Nsrc, int Npad,
;                                            u16* __restrict__ dst, int& ctr, float* tl, int tid, int bid, int G) {
;     ...
;   for (int t = first; t < T; t += G) {
;     const int k0 = (t / nn) * 64, n0 = (t % nn) * 64;
;     {
;       const int r = tid >> 4, c4 = (tid & 15) * 4;
; #pragma unroll
;       for (int i = 0; i < 2; ++i) {
;         const int rr = r + 32 * i;
;         float4 v = make_float4(0.f, 0.f, 0.f, 0.f);
;         if (n0 + c4 < Nsrc) v = *(const float4*)(src + (size_t)(k0 + rr) * ldsrc + n0 + c4);
;         float* d = tl + rr * 65 + c4;
;         d[0] = v.x; d[1] = v.y; d[2] = v.z; d[3] = v.w;
;       }
;     }
;     __syncthreads();
;     {
;       const int n = tid >> 3, k8 = (tid & 7) * 8;
;       float f[8];
; #pragma unroll
;       for (int i = 0; i < 8; ++i) f[i] = tl[(k8 + i) * 65 + n];
;       u32x4 w = {cvtpk(f[0], f[1]), cvtpk(f[2], f[3]), cvtpk(f[4], f[5]), cvtpk(f[6], f[7])};
;       *(u32x4*)(dst + (size_t)(n0 + n) * K + k0 + k8) = w;
;     }
;     __syncthreads();
.LBB0_738:
	s_or_b64 exec, exec, s[6:7]
	s_waitcnt vmcnt(3)
	ds_write2_b32 v13, v0, v1 offset1:1
	ds_write2_b32 v13, v2, v3 offset0:2 offset1:3
	v_add_u32_e32 v0, 0x2080, v13
	s_waitcnt vmcnt(2)
	ds_write2_b32 v0, v4, v5 offset1:1
	v_add_u32_e32 v0, 0x2088, v13
	ds_write2_b32 v0, v6, v7 offset1:1
	s_waitcnt lgkmcnt(0)
	s_barrier
	ds_read2_b32 v[0:1], v14 offset1:65
	ds_read2_b32 v[2:3], v14 offset0:130 offset1:195
	v_add_u32_e32 v4, 0x400, v14
	s_waitcnt lgkmcnt(1)
	v_cvt_pk_bf16_f32 v0, v0, v1
	s_waitcnt lgkmcnt(0)
	v_cvt_pk_bf16_f32 v1, v2, v3
	ds_read2_b32 v[2:3], v4 offset0:4 offset1:69
	ds_read2_b32 v[4:5], v4 offset0:134 offset1:199
	s_add_i32 s5, s5, s19
	s_waitcnt lgkmcnt(1)
	v_cvt_pk_bf16_f32 v2, v2, v3
	s_waitcnt lgkmcnt(0)
	v_cvt_pk_bf16_f32 v3, v4, v5
	v_add_u32_e32 v4, s5, v12
	v_ashrrev_i32_e32 v5, 31, v4
	v_readlane_b32 s6, v253, 9
	v_lshlrev_b64 v[4:5], 11, v[4:5]
	v_readlane_b32 s7, v253, 10
	s_ashr_i32 s5, s4, 31
	s_add_i32 s18, s18, s8
	v_lshl_add_u64 v[4:5], s[6:7], 0, v[4:5]
	v_lshl_add_u64 v[4:5], s[4:5], 1, v[4:5]
	s_add_i32 s19, s19, s20
	v_lshl_add_u64 v[4:5], v[4:5], 0, v[200:201]
	s_cmpk_lt_i32 s18, 0x400
	global_store_dwordx4 v[4:5], v[0:3], off
	s_barrier
	s_cbranch_scc0 .LBB0_741
.LBB0_739:
	s_ashr_i32 s4, s18, 31
	s_lshr_b32 s4, s4, 26
	s_add_i32 s5, s18, s4
	s_and_b32 s4, s5, 0xffffffc0
	s_lshl_b32 s5, s5, 6
	s_and_b32 s6, s5, 0xfffff000
	s_sub_i32 s5, 0, s6
	s_sub_i32 s6, s19, s6
	v_add_u32_e32 v0, s6, v11
	s_movk_i32 s6, 0x1000
	v_cmp_gt_i32_e32 vcc, s6, v0
	v_mov_b32_e32 v0, 0
	v_mov_b32_e32 v1, 0
	v_mov_b32_e32 v2, 0
	v_mov_b32_e32 v3, 0
	v_mov_b32_e32 v4, 0
	v_mov_b32_e32 v5, 0
	v_mov_b32_e32 v6, 0
	v_mov_b32_e32 v7, 0
	s_and_saveexec_b64 s[6:7], vcc
	s_cbranch_execz .LBB0_738
	v_add_u32_e32 v2, s4, v10
	v_ashrrev_i32_e32 v3, 31, v2
	s_add_i32 s22, s19, s5
	v_lshlrev_b64 v[4:5], 14, v[2:3]
	v_add_u32_e32 v2, 32, v2
	s_ashr_i32 s23, s22, 31
	v_ashrrev_i32_e32 v3, 31, v2
	v_lshl_add_u64 v[0:1], s[22:23], 2, v[8:9]
	v_lshlrev_b64 v[2:3], 14, v[2:3]
	v_lshl_add_u64 v[4:5], v[0:1], 0, v[4:5]
	v_lshl_add_u64 v[6:7], v[0:1], 0, v[2:3]
	s_add_i32 s22, s18, s8
	s_addk_i32 s22, 0x40
	s_lshl_b32 s23, s8, 14
	s_cmpk_le_i32 s22, 0x400
	s_cselect_b32 s23, s23, 0
	v_add_co_u32_e32 v18, vcc, s23, v4
	s_nop 1
	v_addc_co_u32_e32 v19, vcc, 0, v5, vcc
	v_add_co_u32_e32 v20, vcc, s23, v6
	s_nop 1
	v_addc_co_u32_e32 v21, vcc, 0, v7, vcc
	global_load_dwordx4 v[0:3], v[4:5], off
	s_nop 0
	global_load_dwordx4 v[4:7], v[6:7], off
	global_load_dword v248, v[18:19], off
	global_load_dword v249, v[20:21], off
	s_branch .LBB0_738

; __device__ __forceinline__ void cvt_matrix(const float* __restrict__ src, int ldsrc, int K, int Nsrc, int Npad,
;                                            u16* __restrict__ dst, int& ctr, float* tl, int tid, int bid, int G) {
;     ...
;   for (int t = first; t < T; t += G) {
;     const int k0 = (t / nn) * 64, n0 = (t % nn) * 64;
;     {
;       const int r = tid >> 4, c4 = (tid & 15) * 4;
; #pragma unroll
;       for (int i = 0; i < 2; ++i) {
;         const int rr = r + 32 * i;
;         float4 v = make_float4(0.f, 0.f, 0.f, 0.f);
;         if (n0 + c4 < Nsrc) v = *(const float4*)(src + (size_t)(k0 + rr) * ldsrc + n0 + c4);
;         float* d = tl + rr * 65 + c4;
;         d[0] = v.x; d[1] = v.y; d[2] = v.z; d[3] = v.w;
;       }
;     }
;     __syncthreads();
;     {
;       const int n = tid >> 3, k8 = (tid & 7) * 8;
;       float f[8];
; #pragma unroll
;       for (int i = 0; i < 8; ++i) f[i] = tl[(k8 + i) * 65 + n];
;       u32x4 w = {cvtpk(f[0], f[1]), cvtpk(f[2], f[3]), cvtpk(f[4], f[5]), cvtpk(f[6], f[7])};
;       *(u32x4*)(dst + (size_t)(n0 + n) * K + k0 + k8) = w;
;     }
;     __syncthreads();
.LBB0_743:
	s_or_b64 exec, exec, s[4:5]
	s_waitcnt vmcnt(3)
	ds_write2_b32 v13, v0, v1 offset1:1
	ds_write2_b32 v13, v2, v3 offset0:2 offset1:3
	v_add_u32_e32 v0, 0x2080, v13
	s_waitcnt vmcnt(2)
	ds_write2_b32 v0, v4, v5 offset1:1
	v_add_u32_e32 v0, 0x2088, v13
	ds_write2_b32 v0, v6, v7 offset1:1
	s_waitcnt lgkmcnt(0)
	s_barrier
	ds_read2_b32 v[0:1], v14 offset1:65
	ds_read2_b32 v[2:3], v14 offset0:130 offset1:195
	v_add_u32_e32 v4, 0x400, v14
	s_waitcnt lgkmcnt(1)
	v_cvt_pk_bf16_f32 v0, v0, v1
	s_waitcnt lgkmcnt(0)
	v_cvt_pk_bf16_f32 v1, v2, v3
	ds_read2_b32 v[2:3], v4 offset0:4 offset1:69
	ds_read2_b32 v[4:5], v4 offset0:134 offset1:199
	s_add_i32 s1, s1, s7
	s_waitcnt lgkmcnt(1)
	v_cvt_pk_bf16_f32 v2, v2, v3
	s_waitcnt lgkmcnt(0)
	v_cvt_pk_bf16_f32 v3, v4, v5
	v_add_u32_e32 v4, s1, v12
	v_ashrrev_i32_e32 v5, 31, v4
	v_readlane_b32 s4, v253, 21
	v_lshlrev_b64 v[4:5], 13, v[4:5]
	v_readlane_b32 s5, v253, 22
	s_ashr_i32 s1, s0, 31
	s_add_i32 s6, s6, s8
	v_lshl_add_u64 v[4:5], s[4:5], 0, v[4:5]
	v_lshl_add_u64 v[4:5], s[0:1], 1, v[4:5]
	s_add_i32 s7, s7, s9
	v_lshl_add_u64 v[4:5], v[4:5], 0, v[200:201]
	s_cmpk_gt_i32 s6, 0x3ff
	global_store_dwordx4 v[4:5], v[0:3], off
	s_barrier
	s_cbranch_scc1 .LBB0_746
.LBB0_744:
	s_ashr_i32 s0, s6, 31
	s_lshr_b32 s0, s0, 28
	s_add_i32 s0, s6, s0
	s_ashr_i32 s1, s0, 4
	s_lshl_b32 s4, s1, 10
	s_lshl_b32 s0, s1, 6
	s_sub_i32 s1, 0, s4
	s_sub_i32 s4, s7, s4
	v_add_u32_e32 v0, s4, v11
	s_movk_i32 s4, 0x400
	v_cmp_gt_i32_e32 vcc, s4, v0
	v_mov_b32_e32 v0, 0
	v_mov_b32_e32 v1, 0
	v_mov_b32_e32 v2, 0
	v_mov_b32_e32 v3, 0
	v_mov_b32_e32 v4, 0
	v_mov_b32_e32 v5, 0
	v_mov_b32_e32 v6, 0
	v_mov_b32_e32 v7, 0
	s_and_saveexec_b64 s[4:5], vcc
	s_cbranch_execz .LBB0_743
	v_add_u32_e32 v2, s0, v10
	v_ashrrev_i32_e32 v3, 31, v2
	s_add_i32 s10, s7, s1
	v_lshlrev_b64 v[4:5], 12, v[2:3]
	v_add_u32_e32 v2, 32, v2
	s_ashr_i32 s11, s10, 31
	v_ashrrev_i32_e32 v3, 31, v2
	v_lshl_add_u64 v[0:1], s[10:11], 2, v[8:9]
	v_lshlrev_b64 v[2:3], 12, v[2:3]
	v_lshl_add_u64 v[4:5], v[0:1], 0, v[4:5]
	v_lshl_add_u64 v[6:7], v[0:1], 0, v[2:3]
	s_add_i32 s10, s6, s8
	s_addk_i32 s10, 0x40
	s_lshl_b32 s11, s8, 14
	s_cmpk_le_i32 s10, 0x400
	s_cselect_b32 s11, s11, 0
	v_add_co_u32_e32 v18, vcc, s11, v4
	s_nop 1
	v_addc_co_u32_e32 v19, vcc, 0, v5, vcc
	v_add_co_u32_e32 v20, vcc, s11, v6
	s_nop 1
	v_addc_co_u32_e32 v21, vcc, 0, v7, vcc
	global_load_dwordx4 v[0:3], v[4:5], off
	s_nop 0
	global_load_dwordx4 v[4:7], v[6:7], off
	global_load_dword v248, v[18:19], off
	global_load_dword v249, v[20:21], off
	s_branch .LBB0_743
